# hand-written dual-tile K-loop heads aligned to 64-byte boundaries (.p2align 6)
# speedup vs baseline: 1.0021x; 1.0001x over previous
.Lgp1_nosleep:
	v_mov_b32_e32 v56, 0
	v_mov_b32_e32 v57, v56
	v_mov_b32_e32 v58, v56
	v_mov_b32_e32 v59, v56
	v_mov_b32_e32 v48, v56
	v_mov_b32_e32 v49, v56
	v_mov_b32_e32 v50, v56
	v_mov_b32_e32 v51, v56
	v_mov_b32_e32 v60, v56
	v_mov_b32_e32 v61, v56
	v_mov_b32_e32 v62, v56
	v_mov_b32_e32 v63, v56
	v_mov_b32_e32 v52, v56
	v_mov_b32_e32 v53, v56
	v_mov_b32_e32 v54, v56
	v_mov_b32_e32 v55, v56
	v_mov_b32_e32 v40, v56
	v_mov_b32_e32 v41, v56
	v_mov_b32_e32 v42, v56
	v_mov_b32_e32 v43, v56
	v_mov_b32_e32 v32, v56
	v_mov_b32_e32 v33, v56
	v_mov_b32_e32 v34, v56
	v_mov_b32_e32 v35, v56
	v_mov_b32_e32 v44, v56
	v_mov_b32_e32 v45, v56
	v_mov_b32_e32 v46, v56
	v_mov_b32_e32 v47, v56
	v_mov_b32_e32 v36, v56
	v_mov_b32_e32 v37, v56
	v_mov_b32_e32 v38, v56
	v_mov_b32_e32 v39, v56
	v_mov_b32_e32 v24, v56
	v_mov_b32_e32 v25, v56
	v_mov_b32_e32 v26, v56
	v_mov_b32_e32 v27, v56
	v_mov_b32_e32 v16, v56
	v_mov_b32_e32 v17, v56
	v_mov_b32_e32 v18, v56
	v_mov_b32_e32 v19, v56
	v_mov_b32_e32 v28, v56
	v_mov_b32_e32 v29, v56
	v_mov_b32_e32 v30, v56
	v_mov_b32_e32 v31, v56
	v_mov_b32_e32 v20, v56
	v_mov_b32_e32 v21, v56
	v_mov_b32_e32 v22, v56
	v_mov_b32_e32 v23, v56
	v_mov_b32_e32 v8, v56
	v_mov_b32_e32 v9, v56
	v_mov_b32_e32 v10, v56
	v_mov_b32_e32 v11, v56
	v_mov_b32_e32 v0, v56
	v_mov_b32_e32 v1, v56
	v_mov_b32_e32 v2, v56
	v_mov_b32_e32 v3, v56
	v_mov_b32_e32 v12, v56
	v_mov_b32_e32 v13, v56
	v_mov_b32_e32 v14, v56
	v_mov_b32_e32 v15, v56
	v_mov_b32_e32 v4, v56
	v_mov_b32_e32 v5, v56
	v_mov_b32_e32 v6, v56
	v_mov_b32_e32 v7, v56
	v_mov_b32_e32 v116, v56
	v_mov_b32_e32 v117, v56
	v_mov_b32_e32 v118, v56
	v_mov_b32_e32 v119, v56
	v_mov_b32_e32 v120, v56
	v_mov_b32_e32 v121, v56
	v_mov_b32_e32 v122, v56
	v_mov_b32_e32 v123, v56
	v_mov_b32_e32 v124, v56
	v_mov_b32_e32 v125, v56
	v_mov_b32_e32 v126, v56
	v_mov_b32_e32 v127, v56
	v_mov_b32_e32 v128, v56
	v_mov_b32_e32 v129, v56
	v_mov_b32_e32 v130, v56
	v_mov_b32_e32 v131, v56
	v_mov_b32_e32 v132, v56
	v_mov_b32_e32 v133, v56
	v_mov_b32_e32 v134, v56
	v_mov_b32_e32 v135, v56
	v_mov_b32_e32 v136, v56
	v_mov_b32_e32 v137, v56
	v_mov_b32_e32 v138, v56
	v_mov_b32_e32 v139, v56
	v_mov_b32_e32 v140, v56
	v_mov_b32_e32 v141, v56
	v_mov_b32_e32 v142, v56
	v_mov_b32_e32 v143, v56
	v_mov_b32_e32 v144, v56
	v_mov_b32_e32 v145, v56
	v_mov_b32_e32 v146, v56
	v_mov_b32_e32 v147, v56
	v_mov_b32_e32 v148, v56
	v_mov_b32_e32 v149, v56
	v_mov_b32_e32 v150, v56
	v_mov_b32_e32 v151, v56
	v_mov_b32_e32 v152, v56
	v_mov_b32_e32 v153, v56
	v_mov_b32_e32 v154, v56
	v_mov_b32_e32 v155, v56
	v_mov_b32_e32 v156, v56
	v_mov_b32_e32 v157, v56
	v_mov_b32_e32 v158, v56
	v_mov_b32_e32 v159, v56
	v_mov_b32_e32 v160, v56
	v_mov_b32_e32 v161, v56
	v_mov_b32_e32 v162, v56
	v_mov_b32_e32 v163, v56
	v_mov_b32_e32 v164, v56
	v_mov_b32_e32 v165, v56
	v_mov_b32_e32 v166, v56
	v_mov_b32_e32 v167, v56
	v_mov_b32_e32 v172, v56
	v_mov_b32_e32 v173, v56
	v_mov_b32_e32 v174, v56
	v_mov_b32_e32 v175, v56
	v_mov_b32_e32 v176, v56
	v_mov_b32_e32 v177, v56
	v_mov_b32_e32 v178, v56
	v_mov_b32_e32 v179, v56
	v_mov_b32_e32 v180, v56
	v_mov_b32_e32 v181, v56
	v_mov_b32_e32 v182, v56
	v_mov_b32_e32 v183, v56
	s_mov_b32 s94, 0
	.p2align 6

.Lp6_dec:
	s_load_dwordx2 s[22:23], s[0:1], 0x60
	s_load_dwordx2 s[24:25], s[0:1], 0xe0
	s_load_dwordx2 s[26:27], s[0:1], 0xd8
	s_mov_b32 s3, 0x7fff
	v_mov_b32_e32 v242, 1
	v_lshlrev_b32_e32 v243, 4, v168
	v_bfe_u32 v249, v168, 6, 1
	v_bfe_u32 v250, v168, 4, 2
	v_lshlrev_b32_e32 v250, 4, v250
	v_lshl_or_b32 v244, v249, 8, v250
	s_lshl_b32 s71, s74, 9
	s_and_b32 s72, s2, 7
	s_lshl_b32 s72, s72, 23
	s_lshr_b32 s73, s2, 3
	s_lshl_b32 s73, s73, 17
	s_add_u32 s72, s72, s73
	s_waitcnt lgkmcnt(0)
	s_add_u32 s22, s22, s71
	s_addc_u32 s23, s23, 0
	s_add_u32 s24, s24, s72
	s_addc_u32 s25, s25, 0
	v_and_b32_e32 v236, 15, v168
	v_lshrrev_b32_e32 v237, 1, v236
	v_bfe_u32 v238, v168, 4, 2
	v_xor_b32_e32 v237, v237, v238
	v_lshlrev_b32_e32 v237, 4, v237
	v_lshl_or_b32 v236, v236, 7, v237
	v_xor_b32_e32 v237, 64, v236
	v_add_u32_e32 v236, 16, v236
	v_add_u32_e32 v237, 16, v237
	v_bfe_u32 v238, v168, 7, 1
	v_lshl_add_u32 v240, v238, 13, v237
	v_lshl_add_u32 v238, v238, 13, v236
	v_bfe_u32 v239, v168, 6, 1
	v_lshl_add_u32 v241, v239, 13, v237
	v_lshl_add_u32 v239, v239, 13, v236
	v_lshrrev_b32_e32 v236, 3, v168
	v_lshrrev_b32_e32 v237, 4, v168
	v_xor_b32_e32 v237, v237, v168
	v_and_b32_e32 v237, 7, v237
	v_lshlrev_b32_e32 v237, 4, v237
	v_lshl_or_b32 v232, v236, 11, v237
	v_add_u32_e32 v233, 0x10000, v232
	v_add_u32_e32 v234, 0x20000, v232
	v_add_u32_e32 v235, 0x30000, v232
	s_load_dwordx2 s[90:91], s[0:1], 0xa0
	s_load_dwordx2 s[92:93], s[0:1], 0xa8
	v_lshrrev_b32_e32 v237, 6, v168
	s_nop 1
	v_readfirstlane_b32 s97, v237
	s_nop 3
	s_lshl_b32 s96, s97, 10
	s_add_u32 s96, s96, 16
	s_add_u32 s94, s81, s80
	s_cmp_lt_i32 s94, s82
	s_cselect_b32 s95, 1, 0
	s_cmp_lg_u64 s[20:21], 0
	s_cselect_b32 s95, 0, s95
	s_cmp_ge_u32 s94, 0x40
	s_cselect_b32 s97, 1, 0
	s_mul_i32 s100, s97, 0x40
	s_sub_u32 s100, s94, s100
	s_lshr_b32 s101, s100, 3
	s_and_b32 s100, s100, 7
	s_lshl_b32 s97, s97, 3
	s_add_u32 s100, s100, s97
	s_add_u32 s100, s100, s79
	s_cmp_lg_u32 s101, s74
	s_cselect_b32 s95, 0, s95
	s_cmp_eq_u32 s95, 1
	s_cselect_b32 s101, s100, s70
	s_mov_b32 s97, s101
	s_waitcnt lgkmcnt(0)
	s_lshl_b32 s94, s74, 18
	s_add_u32 s94, s94, 0xc40000
	s_add_u32 s98, s92, s94
	s_addc_u32 s99, s93, 0
	s_lshl_b32 s101, s101, 18
	s_add_u32 s92, s90, s101
	s_addc_u32 s93, s91, 0
	s_lshl_b32 s94, s70, 18
	s_add_u32 s90, s90, s94
	s_addc_u32 s91, s91, 0
	s_mov_b64 s[100:101], s[90:91]
	s_mov_b64 s[90:91], s[98:99]
	s_mov_b64 s[98:99], s[92:93]
	s_mov_b64 s[92:93], s[100:101]
	s_waitcnt vmcnt(0)
	s_barrier
	s_add_u32 m0, s96, 0x0
	s_nop 0
	global_load_lds_dwordx4 v232, s[90:91]
	s_add_u32 m0, s96, 0x1000
	s_nop 0
	global_load_lds_dwordx4 v233, s[90:91]
	s_add_u32 m0, s96, 0x2000
	s_nop 0
	global_load_lds_dwordx4 v234, s[90:91]
	s_add_u32 m0, s96, 0x3000
	s_nop 0
	global_load_lds_dwordx4 v235, s[90:91]
	s_add_u32 m0, s96, 0x8000
	s_nop 0
	global_load_lds_dwordx4 v232, s[92:93]
	s_add_u32 m0, s96, 0x9000
	s_nop 0
	global_load_lds_dwordx4 v233, s[92:93]
	s_add_u32 m0, s96, 0xa000
	s_nop 0
	global_load_lds_dwordx4 v234, s[92:93]
	s_add_u32 m0, s96, 0xb000
	s_nop 0
	global_load_lds_dwordx4 v235, s[92:93]
	s_add_u32 m0, s96, 0xc000
	s_nop 0
	global_load_lds_dwordx4 v232, s[98:99]
	s_add_u32 m0, s96, 0xd000
	s_nop 0
	global_load_lds_dwordx4 v233, s[98:99]
	s_add_u32 m0, s96, 0xe000
	s_nop 0
	global_load_lds_dwordx4 v234, s[98:99]
	s_add_u32 m0, s96, 0xf000
	s_nop 0
	global_load_lds_dwordx4 v235, s[98:99]
	s_add_u32 s90, s90, 0x80
	s_addc_u32 s91, s91, 0
	s_add_u32 s92, s92, 0x80
	s_addc_u32 s93, s93, 0
	s_add_u32 s98, s98, 0x80
	s_addc_u32 s99, s99, 0
	v_mov_b32_e32 v0, 0
	v_mov_b32_e32 v1, v0
	v_mov_b32_e32 v2, v0
	v_mov_b32_e32 v3, v0
	v_mov_b32_e32 v4, v0
	v_mov_b32_e32 v5, v0
	v_mov_b32_e32 v6, v0
	v_mov_b32_e32 v7, v0
	v_mov_b32_e32 v8, v0
	v_mov_b32_e32 v9, v0
	v_mov_b32_e32 v10, v0
	v_mov_b32_e32 v11, v0
	v_mov_b32_e32 v12, v0
	v_mov_b32_e32 v13, v0
	v_mov_b32_e32 v14, v0
	v_mov_b32_e32 v15, v0
	v_mov_b32_e32 v16, v0
	v_mov_b32_e32 v17, v0
	v_mov_b32_e32 v18, v0
	v_mov_b32_e32 v19, v0
	v_mov_b32_e32 v20, v0
	v_mov_b32_e32 v21, v0
	v_mov_b32_e32 v22, v0
	v_mov_b32_e32 v23, v0
	v_mov_b32_e32 v24, v0
	v_mov_b32_e32 v25, v0
	v_mov_b32_e32 v26, v0
	v_mov_b32_e32 v27, v0
	v_mov_b32_e32 v28, v0
	v_mov_b32_e32 v29, v0
	v_mov_b32_e32 v30, v0
	v_mov_b32_e32 v31, v0
	v_mov_b32_e32 v32, v0
	v_mov_b32_e32 v33, v0
	v_mov_b32_e32 v34, v0
	v_mov_b32_e32 v35, v0
	v_mov_b32_e32 v36, v0
	v_mov_b32_e32 v37, v0
	v_mov_b32_e32 v38, v0
	v_mov_b32_e32 v39, v0
	v_mov_b32_e32 v40, v0
	v_mov_b32_e32 v41, v0
	v_mov_b32_e32 v42, v0
	v_mov_b32_e32 v43, v0
	v_mov_b32_e32 v44, v0
	v_mov_b32_e32 v45, v0
	v_mov_b32_e32 v46, v0
	v_mov_b32_e32 v47, v0
	v_mov_b32_e32 v48, v0
	v_mov_b32_e32 v49, v0
	v_mov_b32_e32 v50, v0
	v_mov_b32_e32 v51, v0
	v_mov_b32_e32 v52, v0
	v_mov_b32_e32 v53, v0
	v_mov_b32_e32 v54, v0
	v_mov_b32_e32 v55, v0
	v_mov_b32_e32 v56, v0
	v_mov_b32_e32 v57, v0
	v_mov_b32_e32 v58, v0
	v_mov_b32_e32 v59, v0
	v_mov_b32_e32 v60, v0
	v_mov_b32_e32 v61, v0
	v_mov_b32_e32 v62, v0
	v_mov_b32_e32 v63, v0
	v_mov_b32_e32 v64, v0
	v_mov_b32_e32 v65, v0
	v_mov_b32_e32 v66, v0
	v_mov_b32_e32 v67, v0
	v_mov_b32_e32 v68, v0
	v_mov_b32_e32 v69, v0
	v_mov_b32_e32 v70, v0
	v_mov_b32_e32 v71, v0
	v_mov_b32_e32 v72, v0
	v_mov_b32_e32 v73, v0
	v_mov_b32_e32 v74, v0
	v_mov_b32_e32 v75, v0
	v_mov_b32_e32 v76, v0
	v_mov_b32_e32 v77, v0
	v_mov_b32_e32 v78, v0
	v_mov_b32_e32 v79, v0
	v_mov_b32_e32 v80, v0
	v_mov_b32_e32 v81, v0
	v_mov_b32_e32 v82, v0
	v_mov_b32_e32 v83, v0
	v_mov_b32_e32 v84, v0
	v_mov_b32_e32 v85, v0
	v_mov_b32_e32 v86, v0
	v_mov_b32_e32 v87, v0
	v_mov_b32_e32 v88, v0
	v_mov_b32_e32 v89, v0
	v_mov_b32_e32 v90, v0
	v_mov_b32_e32 v91, v0
	v_mov_b32_e32 v92, v0
	v_mov_b32_e32 v93, v0
	v_mov_b32_e32 v94, v0
	v_mov_b32_e32 v95, v0
	v_mov_b32_e32 v96, v0
	v_mov_b32_e32 v97, v0
	v_mov_b32_e32 v98, v0
	v_mov_b32_e32 v99, v0
	v_mov_b32_e32 v100, v0
	v_mov_b32_e32 v101, v0
	v_mov_b32_e32 v102, v0
	v_mov_b32_e32 v103, v0
	v_mov_b32_e32 v104, v0
	v_mov_b32_e32 v105, v0
	v_mov_b32_e32 v106, v0
	v_mov_b32_e32 v107, v0
	v_mov_b32_e32 v108, v0
	v_mov_b32_e32 v109, v0
	v_mov_b32_e32 v110, v0
	v_mov_b32_e32 v111, v0
	v_mov_b32_e32 v112, v0
	v_mov_b32_e32 v113, v0
	v_mov_b32_e32 v114, v0
	v_mov_b32_e32 v115, v0
	v_mov_b32_e32 v116, v0
	v_mov_b32_e32 v117, v0
	v_mov_b32_e32 v118, v0
	v_mov_b32_e32 v119, v0
	v_mov_b32_e32 v120, v0
	v_mov_b32_e32 v121, v0
	v_mov_b32_e32 v122, v0
	v_mov_b32_e32 v123, v0
	v_mov_b32_e32 v124, v0
	v_mov_b32_e32 v125, v0
	v_mov_b32_e32 v126, v0
	v_mov_b32_e32 v127, v0
	s_mov_b32 s94, 0
	.p2align 6

.Lp6a_epdone:
	v_lshrrev_b32_e32 v236, 3, v168
	v_lshrrev_b32_e32 v237, 4, v168
	v_xor_b32_e32 v237, v237, v168
	v_and_b32_e32 v237, 7, v237
	v_lshlrev_b32_e32 v237, 4, v237
	v_lshl_or_b32 v232, v236, 11, v237
	v_add_u32_e32 v233, 0x10000, v232
	v_add_u32_e32 v234, 0x20000, v232
	v_add_u32_e32 v235, 0x30000, v232
	s_load_dwordx2 s[90:91], s[0:1], 0xa0
	s_load_dwordx2 s[92:93], s[0:1], 0xb0
	v_lshrrev_b32_e32 v237, 6, v168
	s_nop 1
	v_readfirstlane_b32 s97, v237
	s_nop 3
	s_lshl_b32 s96, s97, 10
	s_add_u32 s96, s96, 16
	s_add_u32 s94, s81, s80
	s_cmp_lt_i32 s94, s82
	s_cselect_b32 s95, 1, 0
	s_cmp_lg_u64 s[20:21], 0
	s_cselect_b32 s95, 0, s95
	s_cmp_ge_u32 s94, 0x40
	s_cselect_b32 s97, 1, 0
	s_mul_i32 s100, s97, 0x40
	s_sub_u32 s100, s94, s100
	s_lshr_b32 s101, s100, 3
	s_and_b32 s100, s100, 7
	s_lshl_b32 s97, s97, 3
	s_add_u32 s100, s100, s97
	s_add_u32 s100, s100, s79
	s_cmp_lg_u32 s101, s74
	s_cselect_b32 s95, 0, s95
	s_cmp_eq_u32 s95, 1
	s_cselect_b32 s101, s100, s70
	s_mov_b32 s97, s101
	s_waitcnt lgkmcnt(0)
	s_lshl_b32 s94, s74, 18
	s_add_u32 s98, s92, s94
	s_addc_u32 s99, s93, 0
	s_lshl_b32 s101, s101, 18
	s_add_u32 s101, s101, 0x2000000
	s_add_u32 s92, s90, s101
	s_addc_u32 s93, s91, 0
	s_lshl_b32 s94, s70, 18
	s_add_u32 s94, s94, 0x2000000
	s_add_u32 s90, s90, s94
	s_addc_u32 s91, s91, 0
	s_mov_b64 s[100:101], s[90:91]
	s_mov_b64 s[90:91], s[98:99]
	s_mov_b64 s[98:99], s[92:93]
	s_mov_b64 s[92:93], s[100:101]
	s_waitcnt vmcnt(0)
	s_barrier
	s_add_u32 m0, s96, 0x0
	s_nop 0
	global_load_lds_dwordx4 v232, s[90:91]
	s_add_u32 m0, s96, 0x1000
	s_nop 0
	global_load_lds_dwordx4 v233, s[90:91]
	s_add_u32 m0, s96, 0x2000
	s_nop 0
	global_load_lds_dwordx4 v234, s[90:91]
	s_add_u32 m0, s96, 0x3000
	s_nop 0
	global_load_lds_dwordx4 v235, s[90:91]
	s_add_u32 m0, s96, 0x8000
	s_nop 0
	global_load_lds_dwordx4 v232, s[92:93]
	s_add_u32 m0, s96, 0x9000
	s_nop 0
	global_load_lds_dwordx4 v233, s[92:93]
	s_add_u32 m0, s96, 0xa000
	s_nop 0
	global_load_lds_dwordx4 v234, s[92:93]
	s_add_u32 m0, s96, 0xb000
	s_nop 0
	global_load_lds_dwordx4 v235, s[92:93]
	s_add_u32 m0, s96, 0xc000
	s_nop 0
	global_load_lds_dwordx4 v232, s[98:99]
	s_add_u32 m0, s96, 0xd000
	s_nop 0
	global_load_lds_dwordx4 v233, s[98:99]
	s_add_u32 m0, s96, 0xe000
	s_nop 0
	global_load_lds_dwordx4 v234, s[98:99]
	s_add_u32 m0, s96, 0xf000
	s_nop 0
	global_load_lds_dwordx4 v235, s[98:99]
	s_add_u32 s90, s90, 0x80
	s_addc_u32 s91, s91, 0
	s_add_u32 s92, s92, 0x80
	s_addc_u32 s93, s93, 0
	s_add_u32 s98, s98, 0x80
	s_addc_u32 s99, s99, 0
	v_mov_b32_e32 v0, 0
	v_mov_b32_e32 v1, v0
	v_mov_b32_e32 v2, v0
	v_mov_b32_e32 v3, v0
	v_mov_b32_e32 v4, v0
	v_mov_b32_e32 v5, v0
	v_mov_b32_e32 v6, v0
	v_mov_b32_e32 v7, v0
	v_mov_b32_e32 v8, v0
	v_mov_b32_e32 v9, v0
	v_mov_b32_e32 v10, v0
	v_mov_b32_e32 v11, v0
	v_mov_b32_e32 v12, v0
	v_mov_b32_e32 v13, v0
	v_mov_b32_e32 v14, v0
	v_mov_b32_e32 v15, v0
	v_mov_b32_e32 v16, v0
	v_mov_b32_e32 v17, v0
	v_mov_b32_e32 v18, v0
	v_mov_b32_e32 v19, v0
	v_mov_b32_e32 v20, v0
	v_mov_b32_e32 v21, v0
	v_mov_b32_e32 v22, v0
	v_mov_b32_e32 v23, v0
	v_mov_b32_e32 v24, v0
	v_mov_b32_e32 v25, v0
	v_mov_b32_e32 v26, v0
	v_mov_b32_e32 v27, v0
	v_mov_b32_e32 v28, v0
	v_mov_b32_e32 v29, v0
	v_mov_b32_e32 v30, v0
	v_mov_b32_e32 v31, v0
	v_mov_b32_e32 v32, v0
	v_mov_b32_e32 v33, v0
	v_mov_b32_e32 v34, v0
	v_mov_b32_e32 v35, v0
	v_mov_b32_e32 v36, v0
	v_mov_b32_e32 v37, v0
	v_mov_b32_e32 v38, v0
	v_mov_b32_e32 v39, v0
	v_mov_b32_e32 v40, v0
	v_mov_b32_e32 v41, v0
	v_mov_b32_e32 v42, v0
	v_mov_b32_e32 v43, v0
	v_mov_b32_e32 v44, v0
	v_mov_b32_e32 v45, v0
	v_mov_b32_e32 v46, v0
	v_mov_b32_e32 v47, v0
	v_mov_b32_e32 v48, v0
	v_mov_b32_e32 v49, v0
	v_mov_b32_e32 v50, v0
	v_mov_b32_e32 v51, v0
	v_mov_b32_e32 v52, v0
	v_mov_b32_e32 v53, v0
	v_mov_b32_e32 v54, v0
	v_mov_b32_e32 v55, v0
	v_mov_b32_e32 v56, v0
	v_mov_b32_e32 v57, v0
	v_mov_b32_e32 v58, v0
	v_mov_b32_e32 v59, v0
	v_mov_b32_e32 v60, v0
	v_mov_b32_e32 v61, v0
	v_mov_b32_e32 v62, v0
	v_mov_b32_e32 v63, v0
	v_mov_b32_e32 v64, v0
	v_mov_b32_e32 v65, v0
	v_mov_b32_e32 v66, v0
	v_mov_b32_e32 v67, v0
	v_mov_b32_e32 v68, v0
	v_mov_b32_e32 v69, v0
	v_mov_b32_e32 v70, v0
	v_mov_b32_e32 v71, v0
	v_mov_b32_e32 v72, v0
	v_mov_b32_e32 v73, v0
	v_mov_b32_e32 v74, v0
	v_mov_b32_e32 v75, v0
	v_mov_b32_e32 v76, v0
	v_mov_b32_e32 v77, v0
	v_mov_b32_e32 v78, v0
	v_mov_b32_e32 v79, v0
	v_mov_b32_e32 v80, v0
	v_mov_b32_e32 v81, v0
	v_mov_b32_e32 v82, v0
	v_mov_b32_e32 v83, v0
	v_mov_b32_e32 v84, v0
	v_mov_b32_e32 v85, v0
	v_mov_b32_e32 v86, v0
	v_mov_b32_e32 v87, v0
	v_mov_b32_e32 v88, v0
	v_mov_b32_e32 v89, v0
	v_mov_b32_e32 v90, v0
	v_mov_b32_e32 v91, v0
	v_mov_b32_e32 v92, v0
	v_mov_b32_e32 v93, v0
	v_mov_b32_e32 v94, v0
	v_mov_b32_e32 v95, v0
	v_mov_b32_e32 v96, v0
	v_mov_b32_e32 v97, v0
	v_mov_b32_e32 v98, v0
	v_mov_b32_e32 v99, v0
	v_mov_b32_e32 v100, v0
	v_mov_b32_e32 v101, v0
	v_mov_b32_e32 v102, v0
	v_mov_b32_e32 v103, v0
	v_mov_b32_e32 v104, v0
	v_mov_b32_e32 v105, v0
	v_mov_b32_e32 v106, v0
	v_mov_b32_e32 v107, v0
	v_mov_b32_e32 v108, v0
	v_mov_b32_e32 v109, v0
	v_mov_b32_e32 v110, v0
	v_mov_b32_e32 v111, v0
	v_mov_b32_e32 v112, v0
	v_mov_b32_e32 v113, v0
	v_mov_b32_e32 v114, v0
	v_mov_b32_e32 v115, v0
	v_mov_b32_e32 v116, v0
	v_mov_b32_e32 v117, v0
	v_mov_b32_e32 v118, v0
	v_mov_b32_e32 v119, v0
	v_mov_b32_e32 v120, v0
	v_mov_b32_e32 v121, v0
	v_mov_b32_e32 v122, v0
	v_mov_b32_e32 v123, v0
	v_mov_b32_e32 v124, v0
	v_mov_b32_e32 v125, v0
	v_mov_b32_e32 v126, v0
	v_mov_b32_e32 v127, v0
	s_mov_b32 s94, 0
	.p2align 6

.Lp6b_epdone:
	v_lshrrev_b32_e32 v236, 3, v168
	v_lshrrev_b32_e32 v237, 4, v168
	v_xor_b32_e32 v237, v237, v168
	v_and_b32_e32 v237, 7, v237
	v_lshlrev_b32_e32 v237, 4, v237
	v_lshl_or_b32 v232, v236, 11, v237
	v_add_u32_e32 v233, 0x10000, v232
	v_add_u32_e32 v234, 0x20000, v232
	v_add_u32_e32 v235, 0x30000, v232
	s_load_dwordx2 s[90:91], s[0:1], 0x100
	s_load_dwordx2 s[92:93], s[0:1], 0xb8
	v_lshrrev_b32_e32 v237, 6, v168
	s_nop 1
	v_readfirstlane_b32 s97, v237
	s_nop 3
	s_lshl_b32 s96, s97, 10
	s_add_u32 s96, s96, 16
	s_add_u32 s94, s81, s80
	s_cmp_lt_i32 s94, s82
	s_cselect_b32 s95, 1, 0
	s_cmp_lg_u64 s[20:21], 0
	s_cselect_b32 s95, 0, s95
	s_cmp_ge_u32 s94, 0x40
	s_cselect_b32 s97, 1, 0
	s_mul_i32 s100, s97, 0x40
	s_sub_u32 s100, s94, s100
	s_lshr_b32 s101, s100, 3
	s_and_b32 s100, s100, 7
	s_lshl_b32 s97, s97, 3
	s_add_u32 s100, s100, s97
	s_add_u32 s100, s100, s79
	s_cmp_lg_u32 s101, s74
	s_cselect_b32 s95, 0, s95
	s_cmp_eq_u32 s95, 1
	s_cselect_b32 s101, s100, s70
	s_mov_b32 s97, s101
	s_waitcnt lgkmcnt(0)
	s_lshl_b32 s94, s74, 18
	s_add_u32 s98, s92, s94
	s_addc_u32 s99, s93, 0
	s_lshl_b32 s101, s101, 18
	s_add_u32 s92, s90, s101
	s_addc_u32 s93, s91, 0
	s_lshl_b32 s94, s70, 18
	s_add_u32 s90, s90, s94
	s_addc_u32 s91, s91, 0
	s_mov_b64 s[100:101], s[90:91]
	s_mov_b64 s[90:91], s[98:99]
	s_mov_b64 s[98:99], s[92:93]
	s_mov_b64 s[92:93], s[100:101]
	s_waitcnt vmcnt(0)
	s_barrier
	s_add_u32 m0, s96, 0x0
	s_nop 0
	global_load_lds_dwordx4 v232, s[90:91]
	s_add_u32 m0, s96, 0x1000
	s_nop 0
	global_load_lds_dwordx4 v233, s[90:91]
	s_add_u32 m0, s96, 0x2000
	s_nop 0
	global_load_lds_dwordx4 v234, s[90:91]
	s_add_u32 m0, s96, 0x3000
	s_nop 0
	global_load_lds_dwordx4 v235, s[90:91]
	s_add_u32 m0, s96, 0x8000
	s_nop 0
	global_load_lds_dwordx4 v232, s[92:93]
	s_add_u32 m0, s96, 0x9000
	s_nop 0
	global_load_lds_dwordx4 v233, s[92:93]
	s_add_u32 m0, s96, 0xa000
	s_nop 0
	global_load_lds_dwordx4 v234, s[92:93]
	s_add_u32 m0, s96, 0xb000
	s_nop 0
	global_load_lds_dwordx4 v235, s[92:93]
	s_add_u32 m0, s96, 0xc000
	s_nop 0
	global_load_lds_dwordx4 v232, s[98:99]
	s_add_u32 m0, s96, 0xd000
	s_nop 0
	global_load_lds_dwordx4 v233, s[98:99]
	s_add_u32 m0, s96, 0xe000
	s_nop 0
	global_load_lds_dwordx4 v234, s[98:99]
	s_add_u32 m0, s96, 0xf000
	s_nop 0
	global_load_lds_dwordx4 v235, s[98:99]
	s_add_u32 s90, s90, 0x80
	s_addc_u32 s91, s91, 0
	s_add_u32 s92, s92, 0x80
	s_addc_u32 s93, s93, 0
	s_add_u32 s98, s98, 0x80
	s_addc_u32 s99, s99, 0
	v_mov_b32_e32 v0, 0
	v_mov_b32_e32 v1, v0
	v_mov_b32_e32 v2, v0
	v_mov_b32_e32 v3, v0
	v_mov_b32_e32 v4, v0
	v_mov_b32_e32 v5, v0
	v_mov_b32_e32 v6, v0
	v_mov_b32_e32 v7, v0
	v_mov_b32_e32 v8, v0
	v_mov_b32_e32 v9, v0
	v_mov_b32_e32 v10, v0
	v_mov_b32_e32 v11, v0
	v_mov_b32_e32 v12, v0
	v_mov_b32_e32 v13, v0
	v_mov_b32_e32 v14, v0
	v_mov_b32_e32 v15, v0
	v_mov_b32_e32 v16, v0
	v_mov_b32_e32 v17, v0
	v_mov_b32_e32 v18, v0
	v_mov_b32_e32 v19, v0
	v_mov_b32_e32 v20, v0
	v_mov_b32_e32 v21, v0
	v_mov_b32_e32 v22, v0
	v_mov_b32_e32 v23, v0
	v_mov_b32_e32 v24, v0
	v_mov_b32_e32 v25, v0
	v_mov_b32_e32 v26, v0
	v_mov_b32_e32 v27, v0
	v_mov_b32_e32 v28, v0
	v_mov_b32_e32 v29, v0
	v_mov_b32_e32 v30, v0
	v_mov_b32_e32 v31, v0
	v_mov_b32_e32 v32, v0
	v_mov_b32_e32 v33, v0
	v_mov_b32_e32 v34, v0
	v_mov_b32_e32 v35, v0
	v_mov_b32_e32 v36, v0
	v_mov_b32_e32 v37, v0
	v_mov_b32_e32 v38, v0
	v_mov_b32_e32 v39, v0
	v_mov_b32_e32 v40, v0
	v_mov_b32_e32 v41, v0
	v_mov_b32_e32 v42, v0
	v_mov_b32_e32 v43, v0
	v_mov_b32_e32 v44, v0
	v_mov_b32_e32 v45, v0
	v_mov_b32_e32 v46, v0
	v_mov_b32_e32 v47, v0
	v_mov_b32_e32 v48, v0
	v_mov_b32_e32 v49, v0
	v_mov_b32_e32 v50, v0
	v_mov_b32_e32 v51, v0
	v_mov_b32_e32 v52, v0
	v_mov_b32_e32 v53, v0
	v_mov_b32_e32 v54, v0
	v_mov_b32_e32 v55, v0
	v_mov_b32_e32 v56, v0
	v_mov_b32_e32 v57, v0
	v_mov_b32_e32 v58, v0
	v_mov_b32_e32 v59, v0
	v_mov_b32_e32 v60, v0
	v_mov_b32_e32 v61, v0
	v_mov_b32_e32 v62, v0
	v_mov_b32_e32 v63, v0
	v_mov_b32_e32 v64, v0
	v_mov_b32_e32 v65, v0
	v_mov_b32_e32 v66, v0
	v_mov_b32_e32 v67, v0
	v_mov_b32_e32 v68, v0
	v_mov_b32_e32 v69, v0
	v_mov_b32_e32 v70, v0
	v_mov_b32_e32 v71, v0
	v_mov_b32_e32 v72, v0
	v_mov_b32_e32 v73, v0
	v_mov_b32_e32 v74, v0
	v_mov_b32_e32 v75, v0
	v_mov_b32_e32 v76, v0
	v_mov_b32_e32 v77, v0
	v_mov_b32_e32 v78, v0
	v_mov_b32_e32 v79, v0
	v_mov_b32_e32 v80, v0
	v_mov_b32_e32 v81, v0
	v_mov_b32_e32 v82, v0
	v_mov_b32_e32 v83, v0
	v_mov_b32_e32 v84, v0
	v_mov_b32_e32 v85, v0
	v_mov_b32_e32 v86, v0
	v_mov_b32_e32 v87, v0
	v_mov_b32_e32 v88, v0
	v_mov_b32_e32 v89, v0
	v_mov_b32_e32 v90, v0
	v_mov_b32_e32 v91, v0
	v_mov_b32_e32 v92, v0
	v_mov_b32_e32 v93, v0
	v_mov_b32_e32 v94, v0
	v_mov_b32_e32 v95, v0
	v_mov_b32_e32 v96, v0
	v_mov_b32_e32 v97, v0
	v_mov_b32_e32 v98, v0
	v_mov_b32_e32 v99, v0
	v_mov_b32_e32 v100, v0
	v_mov_b32_e32 v101, v0
	v_mov_b32_e32 v102, v0
	v_mov_b32_e32 v103, v0
	v_mov_b32_e32 v104, v0
	v_mov_b32_e32 v105, v0
	v_mov_b32_e32 v106, v0
	v_mov_b32_e32 v107, v0
	v_mov_b32_e32 v108, v0
	v_mov_b32_e32 v109, v0
	v_mov_b32_e32 v110, v0
	v_mov_b32_e32 v111, v0
	v_mov_b32_e32 v112, v0
	v_mov_b32_e32 v113, v0
	v_mov_b32_e32 v114, v0
	v_mov_b32_e32 v115, v0
	v_mov_b32_e32 v116, v0
	v_mov_b32_e32 v117, v0
	v_mov_b32_e32 v118, v0
	v_mov_b32_e32 v119, v0
	v_mov_b32_e32 v120, v0
	v_mov_b32_e32 v121, v0
	v_mov_b32_e32 v122, v0
	v_mov_b32_e32 v123, v0
	v_mov_b32_e32 v124, v0
	v_mov_b32_e32 v125, v0
	v_mov_b32_e32 v126, v0
	v_mov_b32_e32 v127, v0
	s_mov_b32 s94, 0
	.p2align 6

.Lp6c_epdone:
	v_lshrrev_b32_e32 v236, 3, v168
	v_lshrrev_b32_e32 v237, 4, v168
	v_xor_b32_e32 v237, v237, v168
	v_and_b32_e32 v237, 7, v237
	v_lshlrev_b32_e32 v237, 4, v237
	v_lshl_or_b32 v232, v236, 11, v237
	v_add_u32_e32 v233, 0x10000, v232
	v_add_u32_e32 v234, 0x20000, v232
	v_add_u32_e32 v235, 0x30000, v232
	s_load_dwordx2 s[90:91], s[0:1], 0xa0
	s_load_dwordx2 s[92:93], s[0:1], 0xa8
	v_lshrrev_b32_e32 v237, 6, v168
	s_nop 1
	v_readfirstlane_b32 s97, v237
	s_nop 3
	s_lshl_b32 s96, s97, 10
	s_add_u32 s96, s96, 16
	s_add_u32 s94, s81, s80
	s_cmp_lt_i32 s94, s82
	s_cselect_b32 s95, 1, 0
	s_cmp_lg_u64 s[20:21], 0
	s_cselect_b32 s95, 0, s95
	s_cmp_ge_u32 s94, 0x40
	s_cselect_b32 s97, 1, 0
	s_mul_i32 s100, s97, 0x40
	s_sub_u32 s100, s94, s100
	s_lshr_b32 s101, s100, 3
	s_and_b32 s100, s100, 7
	s_lshl_b32 s97, s97, 3
	s_add_u32 s100, s100, s97
	s_add_u32 s100, s100, s79
	s_cmp_lg_u32 s101, s74
	s_cselect_b32 s95, 0, s95
	s_cmp_eq_u32 s95, 1
	s_cselect_b32 s101, s100, s70
	s_mov_b32 s97, s101
	s_waitcnt lgkmcnt(0)
	s_lshl_b32 s94, s74, 18
	s_add_u32 s94, s94, 0xe40000
	s_add_u32 s98, s92, s94
	s_addc_u32 s99, s93, 0
	s_lshl_b32 s101, s101, 18
	s_add_u32 s92, s90, s101
	s_addc_u32 s93, s91, 0
	s_lshl_b32 s94, s70, 18
	s_add_u32 s90, s90, s94
	s_addc_u32 s91, s91, 0
	s_mov_b64 s[100:101], s[90:91]
	s_mov_b64 s[90:91], s[98:99]
	s_mov_b64 s[98:99], s[92:93]
	s_mov_b64 s[92:93], s[100:101]
	s_waitcnt vmcnt(0)
	s_barrier
	s_add_u32 m0, s96, 0x0
	s_nop 0
	global_load_lds_dwordx4 v232, s[90:91]
	s_add_u32 m0, s96, 0x1000
	s_nop 0
	global_load_lds_dwordx4 v233, s[90:91]
	s_add_u32 m0, s96, 0x2000
	s_nop 0
	global_load_lds_dwordx4 v234, s[90:91]
	s_add_u32 m0, s96, 0x3000
	s_nop 0
	global_load_lds_dwordx4 v235, s[90:91]
	s_add_u32 m0, s96, 0x8000
	s_nop 0
	global_load_lds_dwordx4 v232, s[92:93]
	s_add_u32 m0, s96, 0x9000
	s_nop 0
	global_load_lds_dwordx4 v233, s[92:93]
	s_add_u32 m0, s96, 0xa000
	s_nop 0
	global_load_lds_dwordx4 v234, s[92:93]
	s_add_u32 m0, s96, 0xb000
	s_nop 0
	global_load_lds_dwordx4 v235, s[92:93]
	s_add_u32 m0, s96, 0xc000
	s_nop 0
	global_load_lds_dwordx4 v232, s[98:99]
	s_add_u32 m0, s96, 0xd000
	s_nop 0
	global_load_lds_dwordx4 v233, s[98:99]
	s_add_u32 m0, s96, 0xe000
	s_nop 0
	global_load_lds_dwordx4 v234, s[98:99]
	s_add_u32 m0, s96, 0xf000
	s_nop 0
	global_load_lds_dwordx4 v235, s[98:99]
	s_add_u32 s90, s90, 0x80
	s_addc_u32 s91, s91, 0
	s_add_u32 s92, s92, 0x80
	s_addc_u32 s93, s93, 0
	s_add_u32 s98, s98, 0x80
	s_addc_u32 s99, s99, 0
	v_mov_b32_e32 v0, 0
	v_mov_b32_e32 v1, v0
	v_mov_b32_e32 v2, v0
	v_mov_b32_e32 v3, v0
	v_mov_b32_e32 v4, v0
	v_mov_b32_e32 v5, v0
	v_mov_b32_e32 v6, v0
	v_mov_b32_e32 v7, v0
	v_mov_b32_e32 v8, v0
	v_mov_b32_e32 v9, v0
	v_mov_b32_e32 v10, v0
	v_mov_b32_e32 v11, v0
	v_mov_b32_e32 v12, v0
	v_mov_b32_e32 v13, v0
	v_mov_b32_e32 v14, v0
	v_mov_b32_e32 v15, v0
	v_mov_b32_e32 v16, v0
	v_mov_b32_e32 v17, v0
	v_mov_b32_e32 v18, v0
	v_mov_b32_e32 v19, v0
	v_mov_b32_e32 v20, v0
	v_mov_b32_e32 v21, v0
	v_mov_b32_e32 v22, v0
	v_mov_b32_e32 v23, v0
	v_mov_b32_e32 v24, v0
	v_mov_b32_e32 v25, v0
	v_mov_b32_e32 v26, v0
	v_mov_b32_e32 v27, v0
	v_mov_b32_e32 v28, v0
	v_mov_b32_e32 v29, v0
	v_mov_b32_e32 v30, v0
	v_mov_b32_e32 v31, v0
	v_mov_b32_e32 v32, v0
	v_mov_b32_e32 v33, v0
	v_mov_b32_e32 v34, v0
	v_mov_b32_e32 v35, v0
	v_mov_b32_e32 v36, v0
	v_mov_b32_e32 v37, v0
	v_mov_b32_e32 v38, v0
	v_mov_b32_e32 v39, v0
	v_mov_b32_e32 v40, v0
	v_mov_b32_e32 v41, v0
	v_mov_b32_e32 v42, v0
	v_mov_b32_e32 v43, v0
	v_mov_b32_e32 v44, v0
	v_mov_b32_e32 v45, v0
	v_mov_b32_e32 v46, v0
	v_mov_b32_e32 v47, v0
	v_mov_b32_e32 v48, v0
	v_mov_b32_e32 v49, v0
	v_mov_b32_e32 v50, v0
	v_mov_b32_e32 v51, v0
	v_mov_b32_e32 v52, v0
	v_mov_b32_e32 v53, v0
	v_mov_b32_e32 v54, v0
	v_mov_b32_e32 v55, v0
	v_mov_b32_e32 v56, v0
	v_mov_b32_e32 v57, v0
	v_mov_b32_e32 v58, v0
	v_mov_b32_e32 v59, v0
	v_mov_b32_e32 v60, v0
	v_mov_b32_e32 v61, v0
	v_mov_b32_e32 v62, v0
	v_mov_b32_e32 v63, v0
	v_mov_b32_e32 v64, v0
	v_mov_b32_e32 v65, v0
	v_mov_b32_e32 v66, v0
	v_mov_b32_e32 v67, v0
	v_mov_b32_e32 v68, v0
	v_mov_b32_e32 v69, v0
	v_mov_b32_e32 v70, v0
	v_mov_b32_e32 v71, v0
	v_mov_b32_e32 v72, v0
	v_mov_b32_e32 v73, v0
	v_mov_b32_e32 v74, v0
	v_mov_b32_e32 v75, v0
	v_mov_b32_e32 v76, v0
	v_mov_b32_e32 v77, v0
	v_mov_b32_e32 v78, v0
	v_mov_b32_e32 v79, v0
	v_mov_b32_e32 v80, v0
	v_mov_b32_e32 v81, v0
	v_mov_b32_e32 v82, v0
	v_mov_b32_e32 v83, v0
	v_mov_b32_e32 v84, v0
	v_mov_b32_e32 v85, v0
	v_mov_b32_e32 v86, v0
	v_mov_b32_e32 v87, v0
	v_mov_b32_e32 v88, v0
	v_mov_b32_e32 v89, v0
	v_mov_b32_e32 v90, v0
	v_mov_b32_e32 v91, v0
	v_mov_b32_e32 v92, v0
	v_mov_b32_e32 v93, v0
	v_mov_b32_e32 v94, v0
	v_mov_b32_e32 v95, v0
	v_mov_b32_e32 v96, v0
	v_mov_b32_e32 v97, v0
	v_mov_b32_e32 v98, v0
	v_mov_b32_e32 v99, v0
	v_mov_b32_e32 v100, v0
	v_mov_b32_e32 v101, v0
	v_mov_b32_e32 v102, v0
	v_mov_b32_e32 v103, v0
	v_mov_b32_e32 v104, v0
	v_mov_b32_e32 v105, v0
	v_mov_b32_e32 v106, v0
	v_mov_b32_e32 v107, v0
	v_mov_b32_e32 v108, v0
	v_mov_b32_e32 v109, v0
	v_mov_b32_e32 v110, v0
	v_mov_b32_e32 v111, v0
	v_mov_b32_e32 v112, v0
	v_mov_b32_e32 v113, v0
	v_mov_b32_e32 v114, v0
	v_mov_b32_e32 v115, v0
	v_mov_b32_e32 v116, v0
	v_mov_b32_e32 v117, v0
	v_mov_b32_e32 v118, v0
	v_mov_b32_e32 v119, v0
	v_mov_b32_e32 v120, v0
	v_mov_b32_e32 v121, v0
	v_mov_b32_e32 v122, v0
	v_mov_b32_e32 v123, v0
	v_mov_b32_e32 v124, v0
	v_mov_b32_e32 v125, v0
	v_mov_b32_e32 v126, v0
	v_mov_b32_e32 v127, v0
	s_mov_b32 s94, 0
	.p2align 6

.Lgp7_nosleep:
	v_mov_b32_e32 v0, 0
	v_mov_b32_e32 v1, v0
	v_mov_b32_e32 v2, v0
	v_mov_b32_e32 v3, v0
	v_mov_b32_e32 v4, v0
	v_mov_b32_e32 v5, v0
	v_mov_b32_e32 v6, v0
	v_mov_b32_e32 v7, v0
	v_mov_b32_e32 v8, v0
	v_mov_b32_e32 v9, v0
	v_mov_b32_e32 v10, v0
	v_mov_b32_e32 v11, v0
	v_mov_b32_e32 v12, v0
	v_mov_b32_e32 v13, v0
	v_mov_b32_e32 v14, v0
	v_mov_b32_e32 v15, v0
	v_mov_b32_e32 v16, v0
	v_mov_b32_e32 v17, v0
	v_mov_b32_e32 v18, v0
	v_mov_b32_e32 v19, v0
	v_mov_b32_e32 v20, v0
	v_mov_b32_e32 v21, v0
	v_mov_b32_e32 v22, v0
	v_mov_b32_e32 v23, v0
	v_mov_b32_e32 v24, v0
	v_mov_b32_e32 v25, v0
	v_mov_b32_e32 v26, v0
	v_mov_b32_e32 v27, v0
	v_mov_b32_e32 v28, v0
	v_mov_b32_e32 v29, v0
	v_mov_b32_e32 v30, v0
	v_mov_b32_e32 v31, v0
	v_mov_b32_e32 v32, v0
	v_mov_b32_e32 v33, v0
	v_mov_b32_e32 v34, v0
	v_mov_b32_e32 v35, v0
	v_mov_b32_e32 v36, v0
	v_mov_b32_e32 v37, v0
	v_mov_b32_e32 v38, v0
	v_mov_b32_e32 v39, v0
	v_mov_b32_e32 v40, v0
	v_mov_b32_e32 v41, v0
	v_mov_b32_e32 v42, v0
	v_mov_b32_e32 v43, v0
	v_mov_b32_e32 v44, v0
	v_mov_b32_e32 v45, v0
	v_mov_b32_e32 v46, v0
	v_mov_b32_e32 v47, v0
	v_mov_b32_e32 v48, v0
	v_mov_b32_e32 v49, v0
	v_mov_b32_e32 v50, v0
	v_mov_b32_e32 v51, v0
	v_mov_b32_e32 v52, v0
	v_mov_b32_e32 v53, v0
	v_mov_b32_e32 v54, v0
	v_mov_b32_e32 v55, v0
	v_mov_b32_e32 v56, v0
	v_mov_b32_e32 v57, v0
	v_mov_b32_e32 v58, v0
	v_mov_b32_e32 v59, v0
	v_mov_b32_e32 v60, v0
	v_mov_b32_e32 v61, v0
	v_mov_b32_e32 v62, v0
	v_mov_b32_e32 v63, v0
	v_mov_b32_e32 v64, v0
	v_mov_b32_e32 v65, v0
	v_mov_b32_e32 v66, v0
	v_mov_b32_e32 v67, v0
	v_mov_b32_e32 v68, v0
	v_mov_b32_e32 v69, v0
	v_mov_b32_e32 v70, v0
	v_mov_b32_e32 v71, v0
	v_mov_b32_e32 v72, v0
	v_mov_b32_e32 v73, v0
	v_mov_b32_e32 v74, v0
	v_mov_b32_e32 v75, v0
	v_mov_b32_e32 v76, v0
	v_mov_b32_e32 v77, v0
	v_mov_b32_e32 v78, v0
	v_mov_b32_e32 v79, v0
	v_mov_b32_e32 v80, v0
	v_mov_b32_e32 v81, v0
	v_mov_b32_e32 v82, v0
	v_mov_b32_e32 v83, v0
	v_mov_b32_e32 v84, v0
	v_mov_b32_e32 v85, v0
	v_mov_b32_e32 v86, v0
	v_mov_b32_e32 v87, v0
	v_mov_b32_e32 v88, v0
	v_mov_b32_e32 v89, v0
	v_mov_b32_e32 v90, v0
	v_mov_b32_e32 v91, v0
	v_mov_b32_e32 v92, v0
	v_mov_b32_e32 v93, v0
	v_mov_b32_e32 v94, v0
	v_mov_b32_e32 v95, v0
	v_mov_b32_e32 v96, v0
	v_mov_b32_e32 v97, v0
	v_mov_b32_e32 v98, v0
	v_mov_b32_e32 v99, v0
	v_mov_b32_e32 v100, v0
	v_mov_b32_e32 v101, v0
	v_mov_b32_e32 v102, v0
	v_mov_b32_e32 v103, v0
	v_mov_b32_e32 v104, v0
	v_mov_b32_e32 v105, v0
	v_mov_b32_e32 v106, v0
	v_mov_b32_e32 v107, v0
	v_mov_b32_e32 v108, v0
	v_mov_b32_e32 v109, v0
	v_mov_b32_e32 v110, v0
	v_mov_b32_e32 v111, v0
	v_mov_b32_e32 v112, v0
	v_mov_b32_e32 v113, v0
	v_mov_b32_e32 v114, v0
	v_mov_b32_e32 v115, v0
	v_mov_b32_e32 v116, v0
	v_mov_b32_e32 v117, v0
	v_mov_b32_e32 v118, v0
	v_mov_b32_e32 v119, v0
	v_mov_b32_e32 v120, v0
	v_mov_b32_e32 v121, v0
	v_mov_b32_e32 v122, v0
	v_mov_b32_e32 v123, v0
	v_mov_b32_e32 v124, v0
	v_mov_b32_e32 v125, v0
	v_mov_b32_e32 v126, v0
	v_mov_b32_e32 v127, v0
	s_mov_b32 s94, 0
	.p2align 6

.Lgp9_nosleep:
	v_mov_b32_e32 v0, 0
	v_mov_b32_e32 v1, v0
	v_mov_b32_e32 v2, v0
	v_mov_b32_e32 v3, v0
	v_mov_b32_e32 v4, v0
	v_mov_b32_e32 v5, v0
	v_mov_b32_e32 v6, v0
	v_mov_b32_e32 v7, v0
	v_mov_b32_e32 v8, v0
	v_mov_b32_e32 v9, v0
	v_mov_b32_e32 v10, v0
	v_mov_b32_e32 v11, v0
	v_mov_b32_e32 v12, v0
	v_mov_b32_e32 v13, v0
	v_mov_b32_e32 v14, v0
	v_mov_b32_e32 v15, v0
	v_mov_b32_e32 v16, v0
	v_mov_b32_e32 v17, v0
	v_mov_b32_e32 v18, v0
	v_mov_b32_e32 v19, v0
	v_mov_b32_e32 v20, v0
	v_mov_b32_e32 v21, v0
	v_mov_b32_e32 v22, v0
	v_mov_b32_e32 v23, v0
	v_mov_b32_e32 v24, v0
	v_mov_b32_e32 v25, v0
	v_mov_b32_e32 v26, v0
	v_mov_b32_e32 v27, v0
	v_mov_b32_e32 v28, v0
	v_mov_b32_e32 v29, v0
	v_mov_b32_e32 v30, v0
	v_mov_b32_e32 v31, v0
	v_mov_b32_e32 v32, v0
	v_mov_b32_e32 v33, v0
	v_mov_b32_e32 v34, v0
	v_mov_b32_e32 v35, v0
	v_mov_b32_e32 v36, v0
	v_mov_b32_e32 v37, v0
	v_mov_b32_e32 v38, v0
	v_mov_b32_e32 v39, v0
	v_mov_b32_e32 v40, v0
	v_mov_b32_e32 v41, v0
	v_mov_b32_e32 v42, v0
	v_mov_b32_e32 v43, v0
	v_mov_b32_e32 v44, v0
	v_mov_b32_e32 v45, v0
	v_mov_b32_e32 v46, v0
	v_mov_b32_e32 v47, v0
	v_mov_b32_e32 v48, v0
	v_mov_b32_e32 v49, v0
	v_mov_b32_e32 v50, v0
	v_mov_b32_e32 v51, v0
	v_mov_b32_e32 v52, v0
	v_mov_b32_e32 v53, v0
	v_mov_b32_e32 v54, v0
	v_mov_b32_e32 v55, v0
	v_mov_b32_e32 v56, v0
	v_mov_b32_e32 v57, v0
	v_mov_b32_e32 v58, v0
	v_mov_b32_e32 v59, v0
	v_mov_b32_e32 v60, v0
	v_mov_b32_e32 v61, v0
	v_mov_b32_e32 v62, v0
	v_mov_b32_e32 v63, v0
	v_mov_b32_e32 v116, v0
	v_mov_b32_e32 v117, v0
	v_mov_b32_e32 v118, v0
	v_mov_b32_e32 v119, v0
	v_mov_b32_e32 v120, v0
	v_mov_b32_e32 v121, v0
	v_mov_b32_e32 v122, v0
	v_mov_b32_e32 v123, v0
	v_mov_b32_e32 v124, v0
	v_mov_b32_e32 v125, v0
	v_mov_b32_e32 v126, v0
	v_mov_b32_e32 v127, v0
	v_mov_b32_e32 v128, v0
	v_mov_b32_e32 v129, v0
	v_mov_b32_e32 v130, v0
	v_mov_b32_e32 v131, v0
	v_mov_b32_e32 v132, v0
	v_mov_b32_e32 v133, v0
	v_mov_b32_e32 v134, v0
	v_mov_b32_e32 v135, v0
	v_mov_b32_e32 v136, v0
	v_mov_b32_e32 v137, v0
	v_mov_b32_e32 v138, v0
	v_mov_b32_e32 v139, v0
	v_mov_b32_e32 v140, v0
	v_mov_b32_e32 v141, v0
	v_mov_b32_e32 v142, v0
	v_mov_b32_e32 v143, v0
	v_mov_b32_e32 v148, v0
	v_mov_b32_e32 v149, v0
	v_mov_b32_e32 v150, v0
	v_mov_b32_e32 v151, v0
	v_mov_b32_e32 v152, v0
	v_mov_b32_e32 v153, v0
	v_mov_b32_e32 v154, v0
	v_mov_b32_e32 v155, v0
	v_mov_b32_e32 v156, v0
	v_mov_b32_e32 v157, v0
	v_mov_b32_e32 v158, v0
	v_mov_b32_e32 v159, v0
	v_mov_b32_e32 v160, v0
	v_mov_b32_e32 v161, v0
	v_mov_b32_e32 v162, v0
	v_mov_b32_e32 v163, v0
	v_mov_b32_e32 v172, v0
	v_mov_b32_e32 v173, v0
	v_mov_b32_e32 v174, v0
	v_mov_b32_e32 v175, v0
	v_mov_b32_e32 v176, v0
	v_mov_b32_e32 v177, v0
	v_mov_b32_e32 v178, v0
	v_mov_b32_e32 v179, v0
	v_mov_b32_e32 v180, v0
	v_mov_b32_e32 v181, v0
	v_mov_b32_e32 v182, v0
	v_mov_b32_e32 v183, v0
	v_mov_b32_e32 v184, v0
	v_mov_b32_e32 v185, v0
	v_mov_b32_e32 v186, v0
	v_mov_b32_e32 v187, v0
	v_mov_b32_e32 v188, v0
	v_mov_b32_e32 v189, v0
	v_mov_b32_e32 v190, v0
	v_mov_b32_e32 v191, v0
	s_mov_b32 s94, 0
	.p2align 6
